# grid barrier flattened: XCD leaders signal per-XCD arrival counters directly (drops TOP/TOPGEN/XGEN hops), same wbl2/inv release-acquire
# speedup vs baseline: 1.0101x; 1.0101x over previous
; DEV unsigned xb_ld(unsigned* p) { return __hip_atomic_load(p, __ATOMIC_RELAXED, __HIP_MEMORY_SCOPE_AGENT); }
; DEV unsigned xb_add(unsigned* p, unsigned v) { return __hip_atomic_fetch_add(p, v, __ATOMIC_RELAXED, __HIP_MEMORY_SCOPE_AGENT); }
; #define XB_SPIN(cond, bar) do { unsigned _sp = 0; while (cond) { __builtin_amdgcn_s_sleep(1); \
;     if ((++_sp & 255u) == 0u) { if (xb_ld(&(bar)[XB_TMO])) break; if (_sp > XB_SPIN_CAP) { atomicAdd(&(bar)[XB_TMO], 1u); break; } } } } while (0)
; DEV void xcd_barrier(const XcdBarrier& b) {
;     ...
;     const unsigned old = xb_add(&bar[XB_XSUB(b.x)], 1u);
;     const unsigned gen = old / nloc;
;     if (old + 1u == (gen + 1u) * nloc) {
;       __builtin_amdgcn_fence(__ATOMIC_RELEASE, "agent");
;       asm volatile("s_waitcnt vmcnt(0)" ::: "memory");
;       const unsigned og = xb_add(&bar[XB_TOP], 1u);
;       const unsigned tg = og / nx;
;       if (og + 1u == (tg + 1u) * nx) xb_add(&bar[XB_TOPGEN], 1u);
;       else XB_SPIN(xb_ld(&bar[XB_TOPGEN]) == tg, bar);
;       __builtin_amdgcn_fence(__ATOMIC_ACQUIRE, "agent");
;       xb_add(&bar[XB_XGEN(b.x)], 1u);
;       asm volatile("s_waitcnt vmcnt(0)" ::: "memory");
;     } else {
;       XB_SPIN(xb_ld(&bar[XB_XGEN(b.x)]) == gen, bar);
;       __builtin_amdgcn_fence(__ATOMIC_ACQUIRE, "agent");
;       asm volatile("s_waitcnt vmcnt(0)" ::: "memory");
;     }
.LBB0_144:
	s_or_b64 exec, exec, s[4:5]
	s_waitcnt vmcnt(0)
	buffer_inv sc1
	s_waitcnt vmcnt(0)

; DEV unsigned xb_ld(unsigned* p) { return __hip_atomic_load(p, __ATOMIC_RELAXED, __HIP_MEMORY_SCOPE_AGENT); }
; DEV unsigned xb_add(unsigned* p, unsigned v) { return __hip_atomic_fetch_add(p, v, __ATOMIC_RELAXED, __HIP_MEMORY_SCOPE_AGENT); }
; #define XB_SPIN(cond, bar) do { unsigned _sp = 0; while (cond) { __builtin_amdgcn_s_sleep(1); \
;     if ((++_sp & 255u) == 0u) { if (xb_ld(&(bar)[XB_TMO])) break; if (_sp > XB_SPIN_CAP) { atomicAdd(&(bar)[XB_TMO], 1u); break; } } } } while (0)
; DEV void xcd_barrier(const XcdBarrier& b) {
;   asm volatile("s_waitcnt vmcnt(0)" ::: "memory");
;   __syncthreads();
;   if (threadIdx.x == 0) {
;     unsigned* bar = b.bar;
;     __builtin_amdgcn_s_waitcnt(0);
;     unsigned nloc = b.st[0], nx = b.st[1];
;     if (nloc == 0u) { xcd_barrier_complete(bar, b.x, nloc, nx); b.st[0] = nloc; b.st[1] = nx; }
;     const unsigned old = xb_add(&bar[XB_XSUB(b.x)], 1u);
;     const unsigned gen = old / nloc;
;     if (old + 1u == (gen + 1u) * nloc) {
;       __builtin_amdgcn_fence(__ATOMIC_RELEASE, "agent");
;       asm volatile("s_waitcnt vmcnt(0)" ::: "memory");
;       const unsigned og = xb_add(&bar[XB_TOP], 1u);
;       const unsigned tg = og / nx;
;       if (og + 1u == (tg + 1u) * nx) xb_add(&bar[XB_TOPGEN], 1u);
;       else XB_SPIN(xb_ld(&bar[XB_TOPGEN]) == tg, bar);
;       __builtin_amdgcn_fence(__ATOMIC_ACQUIRE, "agent");
;       xb_add(&bar[XB_XGEN(b.x)], 1u);
;       asm volatile("s_waitcnt vmcnt(0)" ::: "memory");
;     } else {
;       XB_SPIN(xb_ld(&bar[XB_XGEN(b.x)]) == gen, bar);
;       __builtin_amdgcn_fence(__ATOMIC_ACQUIRE, "agent");
;       asm volatile("s_waitcnt vmcnt(0)" ::: "memory");
;     }
;   }
;   __syncthreads();
; }
.LBB0_203:
	s_waitcnt vmcnt(0)
	s_waitcnt lgkmcnt(0)
	s_barrier
	s_mov_b64 s[0:1], exec
	v_readlane_b32 s14, v251, 1
	v_readlane_b32 s15, v251, 2
	s_and_b64 s[14:15], s[0:1], s[14:15]
	s_mov_b64 exec, s[14:15]
	s_cbranch_execz .LBB0_251
	s_waitcnt vmcnt(0) expcnt(0) lgkmcnt(0)
	ds_read_b32 v2, v193
	ds_read_b32 v0, v194
	global_atomic_add v3, v[176:177], v195, off sc0
	v_readlane_b32 s16, v251, 3
	v_readlane_b32 s17, v251, 4
	s_waitcnt lgkmcnt(0)
	v_cvt_f32_u32_e32 v1, v2
	v_sub_u32_e32 v4, 0, v2
	v_rcp_iflag_f32_e32 v1, v1
	s_add_u32 s16, s16, 0x3600
	s_addc_u32 s17, s17, 0
	v_mul_f32_e32 v1, 0x4f7ffffe, v1
	v_cvt_u32_f32_e32 v1, v1
	v_mul_lo_u32 v4, v4, v1
	v_mul_hi_u32 v4, v1, v4
	v_add_u32_e32 v1, v1, v4
	s_waitcnt vmcnt(0)
	v_mul_hi_u32 v1, v3, v1
	v_mul_lo_u32 v4, v1, v2
	v_sub_u32_e32 v4, v3, v4
	v_add_u32_e32 v5, 1, v1
	v_cmp_ge_u32_e32 vcc, v4, v2
	v_add_u32_e32 v3, 1, v3
	s_nop 1
	v_cndmask_b32_e32 v1, v1, v5, vcc
	v_sub_u32_e32 v5, v4, v2
	v_cndmask_b32_e32 v4, v4, v5, vcc
	v_add_u32_e32 v5, 1, v1
	v_cmp_ge_u32_e32 vcc, v4, v2
	s_nop 1
	v_cndmask_b32_e32 v1, v1, v5, vcc
	v_mul_lo_u32 v4, v2, v1
	v_add_u32_e32 v2, v4, v2
	v_mul_lo_u32 v5, v1, v0
	v_cmp_eq_u32_e32 vcc, v3, v2
	s_and_saveexec_b64 s[14:15], vcc
	s_cbranch_execz Lxb1_poll
	buffer_wbl2 sc1
	s_waitcnt vmcnt(0)
	global_atomic_add v181, v195, s[16:17]
	global_atomic_add v181, v195, s[16:17] offset:32
	global_atomic_add v181, v195, s[16:17] offset:64
	global_atomic_add v181, v195, s[16:17] offset:96
	global_atomic_add v181, v195, s[16:17] offset:128
	global_atomic_add v181, v195, s[16:17] offset:160
	global_atomic_add v181, v195, s[16:17] offset:192
	global_atomic_add v181, v195, s[16:17] offset:224
	global_atomic_add v181, v195, s[16:17] offset:256
	global_atomic_add v181, v195, s[16:17] offset:288
	global_atomic_add v181, v195, s[16:17] offset:320
	global_atomic_add v181, v195, s[16:17] offset:352
	global_atomic_add v181, v195, s[16:17] offset:384
	global_atomic_add v181, v195, s[16:17] offset:416
	global_atomic_add v181, v195, s[16:17] offset:448
	global_atomic_add v181, v195, s[16:17] offset:480
Lxb1_poll:
	s_or_b64 exec, exec, s[14:15]
	v_subrev_u32_e32 v4, s16, v176
	v_add_u32_e32 v4, 0x2200, v4
	v_lshrrev_b32_e32 v4, 3, v4
	s_mov_b32 s6, 0
Lxb1_spin:
	global_load_dword v0, v4, s[16:17] sc1
	s_waitcnt vmcnt(0)
	v_cmp_ge_u32_e32 vcc, v0, v5
	s_cbranch_vccnz Lxb1_done
	s_sleep 1
	s_add_i32 s6, s6, 1
	s_cmp_lt_u32 s6, 0x400000
	s_cbranch_scc1 Lxb1_spin
Lxb1_done:
	buffer_inv sc1

; DEV int bid_() { int t = blockIdx.x; asm volatile("" : "+s"(t)); return t; }
; DEV int gdim_() { int t = gridDim.x; asm volatile("" : "+s"(t)); return t; }
; DEV unsigned xb_ld(unsigned* p) { return __hip_atomic_load(p, __ATOMIC_RELAXED, __HIP_MEMORY_SCOPE_AGENT); }
; DEV unsigned xb_add(unsigned* p, unsigned v) { return __hip_atomic_fetch_add(p, v, __ATOMIC_RELAXED, __HIP_MEMORY_SCOPE_AGENT); }
; #define XB_SPIN(cond, bar) do { unsigned _sp = 0; while (cond) { __builtin_amdgcn_s_sleep(1); \
;     if ((++_sp & 255u) == 0u) { if (xb_ld(&(bar)[XB_TMO])) break; if (_sp > XB_SPIN_CAP) { atomicAdd(&(bar)[XB_TMO], 1u); break; } } } } while (0)
; #define P (*launderP(lp))
; DEV void xcd_barrier(const XcdBarrier& b) {
;   asm volatile("s_waitcnt vmcnt(0)" ::: "memory");
;   __syncthreads();
;   if (threadIdx.x == 0) {
;     unsigned* bar = b.bar;
;     __builtin_amdgcn_s_waitcnt(0);
;     unsigned nloc = b.st[0], nx = b.st[1];
;     if (nloc == 0u) { xcd_barrier_complete(bar, b.x, nloc, nx); b.st[0] = nloc; b.st[1] = nx; }
;     const unsigned old = xb_add(&bar[XB_XSUB(b.x)], 1u);
;     const unsigned gen = old / nloc;
;     if (old + 1u == (gen + 1u) * nloc) {
;       __builtin_amdgcn_fence(__ATOMIC_RELEASE, "agent");
;       asm volatile("s_waitcnt vmcnt(0)" ::: "memory");
;       const unsigned og = xb_add(&bar[XB_TOP], 1u);
;       const unsigned tg = og / nx;
;       if (og + 1u == (tg + 1u) * nx) xb_add(&bar[XB_TOPGEN], 1u);
;       else XB_SPIN(xb_ld(&bar[XB_TOPGEN]) == tg, bar);
;       __builtin_amdgcn_fence(__ATOMIC_ACQUIRE, "agent");
;       xb_add(&bar[XB_XGEN(b.x)], 1u);
;       asm volatile("s_waitcnt vmcnt(0)" ::: "memory");
;     } else {
;       XB_SPIN(xb_ld(&bar[XB_XGEN(b.x)]) == gen, bar);
;       __builtin_amdgcn_fence(__ATOMIC_ACQUIRE, "agent");
;       asm volatile("s_waitcnt vmcnt(0)" ::: "memory");
;     }
;   }
;   __syncthreads();
; }
; __global__ void __launch_bounds__(NTHR, 2) fwd_megakernel(Params Pk) {
;     ...
;       for (int w = bid_(); w < 1024; w += gdim_()) ret_out_item(P, w, ST, smem);
.LBB0_276:
	s_or_b64 exec, exec, s[0:1]
	s_waitcnt vmcnt(0)
	s_waitcnt lgkmcnt(0)
	s_barrier
	s_mov_b64 s[0:1], exec
	v_readlane_b32 s4, v251, 1
	v_readlane_b32 s5, v251, 2
	s_and_b64 s[4:5], s[0:1], s[4:5]
	s_movk_i32 s31, 0x70
	s_mov_b64 exec, s[4:5]
	s_cbranch_execz .LBB0_325
	s_waitcnt vmcnt(0) expcnt(0) lgkmcnt(0)
	ds_read_b32 v2, v193
	ds_read_b32 v0, v194
	global_atomic_add v3, v[176:177], v195, off sc0
	v_readlane_b32 s14, v251, 3
	v_readlane_b32 s15, v251, 4
	s_waitcnt lgkmcnt(0)
	v_cvt_f32_u32_e32 v1, v2
	v_sub_u32_e32 v4, 0, v2
	v_rcp_iflag_f32_e32 v1, v1
	s_add_u32 s14, s14, 0x3600
	s_addc_u32 s15, s15, 0
	v_mul_f32_e32 v1, 0x4f7ffffe, v1
	v_cvt_u32_f32_e32 v1, v1
	v_mul_lo_u32 v4, v4, v1
	v_mul_hi_u32 v4, v1, v4
	v_add_u32_e32 v1, v1, v4
	s_waitcnt vmcnt(0)
	v_mul_hi_u32 v1, v3, v1
	v_mul_lo_u32 v4, v1, v2
	v_sub_u32_e32 v4, v3, v4
	v_add_u32_e32 v5, 1, v1
	v_cmp_ge_u32_e32 vcc, v4, v2
	v_add_u32_e32 v3, 1, v3
	s_nop 1
	v_cndmask_b32_e32 v1, v1, v5, vcc
	v_sub_u32_e32 v5, v4, v2
	v_cndmask_b32_e32 v4, v4, v5, vcc
	v_add_u32_e32 v5, 1, v1
	v_cmp_ge_u32_e32 vcc, v4, v2
	s_nop 1
	v_cndmask_b32_e32 v1, v1, v5, vcc
	v_mul_lo_u32 v4, v2, v1
	v_add_u32_e32 v2, v4, v2
	v_mul_lo_u32 v5, v1, v0
	v_cmp_eq_u32_e32 vcc, v3, v2
	s_and_saveexec_b64 s[4:5], vcc
	s_cbranch_execz Lxb2_poll
	buffer_wbl2 sc1
	s_waitcnt vmcnt(0)
	global_atomic_add v181, v195, s[14:15]
	global_atomic_add v181, v195, s[14:15] offset:32
	global_atomic_add v181, v195, s[14:15] offset:64
	global_atomic_add v181, v195, s[14:15] offset:96
	global_atomic_add v181, v195, s[14:15] offset:128
	global_atomic_add v181, v195, s[14:15] offset:160
	global_atomic_add v181, v195, s[14:15] offset:192
	global_atomic_add v181, v195, s[14:15] offset:224
	global_atomic_add v181, v195, s[14:15] offset:256
	global_atomic_add v181, v195, s[14:15] offset:288
	global_atomic_add v181, v195, s[14:15] offset:320
	global_atomic_add v181, v195, s[14:15] offset:352
	global_atomic_add v181, v195, s[14:15] offset:384
	global_atomic_add v181, v195, s[14:15] offset:416
	global_atomic_add v181, v195, s[14:15] offset:448
	global_atomic_add v181, v195, s[14:15] offset:480
Lxb2_poll:
	s_or_b64 exec, exec, s[4:5]
	v_subrev_u32_e32 v4, s14, v176
	v_add_u32_e32 v4, 0x2200, v4
	v_lshrrev_b32_e32 v4, 3, v4
	s_mov_b32 s6, 0
Lxb2_spin:
	global_load_dword v0, v4, s[14:15] sc1
	s_waitcnt vmcnt(0)
	v_cmp_ge_u32_e32 vcc, v0, v5
	s_cbranch_vccnz Lxb2_done
	s_sleep 1
	s_add_i32 s6, s6, 1
	s_cmp_lt_u32 s6, 0x400000
	s_cbranch_scc1 Lxb2_spin
Lxb2_done:
	buffer_inv sc1
	s_branch .LBB0_325
.LBB0_287:
	s_branch .LBB0_259
.LBB0_325:
	s_or_b64 exec, exec, s[0:1]
	v_readlane_b32 s0, v251, 0
	s_mov_b32 s44, s0
	s_waitcnt lgkmcnt(0)
	s_barrier
	s_cmpk_gt_i32 s44, 0x3ff
	s_cbranch_scc1 .LBB0_349
	s_mov_b64 s[0:1], 0x10000
	v_lshl_add_u64 v[96:97], v[184:185], 0, s[0:1]
	v_writelane_b32 v251, s58, 63
	s_nop 1
	v_writelane_b32 v250, s59, 0
	s_branch .LBB0_328

; DEV unsigned xb_ld(unsigned* p) { return __hip_atomic_load(p, __ATOMIC_RELAXED, __HIP_MEMORY_SCOPE_AGENT); }
; DEV unsigned xb_add(unsigned* p, unsigned v) { return __hip_atomic_fetch_add(p, v, __ATOMIC_RELAXED, __HIP_MEMORY_SCOPE_AGENT); }
; #define XB_SPIN(cond, bar) do { unsigned _sp = 0; while (cond) { __builtin_amdgcn_s_sleep(1); \
;     if ((++_sp & 255u) == 0u) { if (xb_ld(&(bar)[XB_TMO])) break; if (_sp > XB_SPIN_CAP) { atomicAdd(&(bar)[XB_TMO], 1u); break; } } } } while (0)
; DEV void xcd_barrier(const XcdBarrier& b) {
;   asm volatile("s_waitcnt vmcnt(0)" ::: "memory");
;   __syncthreads();
;   if (threadIdx.x == 0) {
;     unsigned* bar = b.bar;
;     __builtin_amdgcn_s_waitcnt(0);
;     unsigned nloc = b.st[0], nx = b.st[1];
;     if (nloc == 0u) { xcd_barrier_complete(bar, b.x, nloc, nx); b.st[0] = nloc; b.st[1] = nx; }
;     const unsigned old = xb_add(&bar[XB_XSUB(b.x)], 1u);
;     const unsigned gen = old / nloc;
;     if (old + 1u == (gen + 1u) * nloc) {
;       __builtin_amdgcn_fence(__ATOMIC_RELEASE, "agent");
;       asm volatile("s_waitcnt vmcnt(0)" ::: "memory");
;       const unsigned og = xb_add(&bar[XB_TOP], 1u);
;       const unsigned tg = og / nx;
;       if (og + 1u == (tg + 1u) * nx) xb_add(&bar[XB_TOPGEN], 1u);
;       else XB_SPIN(xb_ld(&bar[XB_TOPGEN]) == tg, bar);
;       __builtin_amdgcn_fence(__ATOMIC_ACQUIRE, "agent");
;       xb_add(&bar[XB_XGEN(b.x)], 1u);
;       asm volatile("s_waitcnt vmcnt(0)" ::: "memory");
;     } else {
;       XB_SPIN(xb_ld(&bar[XB_XGEN(b.x)]) == gen, bar);
;       __builtin_amdgcn_fence(__ATOMIC_ACQUIRE, "agent");
;       asm volatile("s_waitcnt vmcnt(0)" ::: "memory");
;     }
;   }
;   __syncthreads();
; }
.LBB0_349:
	s_waitcnt vmcnt(0)
	s_waitcnt lgkmcnt(0)
	s_barrier
	s_mov_b64 s[0:1], exec
	v_readlane_b32 s4, v251, 1
	v_readlane_b32 s5, v251, 2
	s_and_b64 s[4:5], s[0:1], s[4:5]
	s_mov_b64 exec, s[4:5]
	s_cbranch_execz .LBB0_397
	s_waitcnt vmcnt(0) expcnt(0) lgkmcnt(0)
	ds_read_b32 v2, v193
	ds_read_b32 v0, v194
	global_atomic_add v3, v[176:177], v195, off sc0
	v_readlane_b32 s14, v251, 3
	v_readlane_b32 s15, v251, 4
	s_waitcnt lgkmcnt(0)
	v_cvt_f32_u32_e32 v1, v2
	v_sub_u32_e32 v4, 0, v2
	v_rcp_iflag_f32_e32 v1, v1
	s_add_u32 s14, s14, 0x3600
	s_addc_u32 s15, s15, 0
	v_mul_f32_e32 v1, 0x4f7ffffe, v1
	v_cvt_u32_f32_e32 v1, v1
	v_mul_lo_u32 v4, v4, v1
	v_mul_hi_u32 v4, v1, v4
	v_add_u32_e32 v1, v1, v4
	s_waitcnt vmcnt(0)
	v_mul_hi_u32 v1, v3, v1
	v_mul_lo_u32 v4, v1, v2
	v_sub_u32_e32 v4, v3, v4
	v_add_u32_e32 v5, 1, v1
	v_cmp_ge_u32_e32 vcc, v4, v2
	v_add_u32_e32 v3, 1, v3
	s_nop 1
	v_cndmask_b32_e32 v1, v1, v5, vcc
	v_sub_u32_e32 v5, v4, v2
	v_cndmask_b32_e32 v4, v4, v5, vcc
	v_add_u32_e32 v5, 1, v1
	v_cmp_ge_u32_e32 vcc, v4, v2
	s_nop 1
	v_cndmask_b32_e32 v1, v1, v5, vcc
	v_mul_lo_u32 v4, v2, v1
	v_add_u32_e32 v2, v4, v2
	v_mul_lo_u32 v5, v1, v0
	v_cmp_eq_u32_e32 vcc, v3, v2
	s_and_saveexec_b64 s[4:5], vcc
	s_cbranch_execz Lxb3_poll
	buffer_wbl2 sc1
	s_waitcnt vmcnt(0)
	global_atomic_add v181, v195, s[14:15]
	global_atomic_add v181, v195, s[14:15] offset:32
	global_atomic_add v181, v195, s[14:15] offset:64
	global_atomic_add v181, v195, s[14:15] offset:96
	global_atomic_add v181, v195, s[14:15] offset:128
	global_atomic_add v181, v195, s[14:15] offset:160
	global_atomic_add v181, v195, s[14:15] offset:192
	global_atomic_add v181, v195, s[14:15] offset:224
	global_atomic_add v181, v195, s[14:15] offset:256
	global_atomic_add v181, v195, s[14:15] offset:288
	global_atomic_add v181, v195, s[14:15] offset:320
	global_atomic_add v181, v195, s[14:15] offset:352
	global_atomic_add v181, v195, s[14:15] offset:384
	global_atomic_add v181, v195, s[14:15] offset:416
	global_atomic_add v181, v195, s[14:15] offset:448
	global_atomic_add v181, v195, s[14:15] offset:480
Lxb3_poll:
	s_or_b64 exec, exec, s[4:5]
	v_subrev_u32_e32 v4, s14, v176
	v_add_u32_e32 v4, 0x2200, v4
	v_lshrrev_b32_e32 v4, 3, v4
	s_mov_b32 s6, 0
Lxb3_spin:
	global_load_dword v0, v4, s[14:15] sc1
	s_waitcnt vmcnt(0)
	v_cmp_ge_u32_e32 vcc, v0, v5
	s_cbranch_vccnz Lxb3_done
	s_sleep 1
	s_add_i32 s6, s6, 1
	s_cmp_lt_u32 s6, 0x400000
	s_cbranch_scc1 Lxb3_spin
Lxb3_done:
	buffer_inv sc1

; DEV unsigned xb_ld(unsigned* p) { return __hip_atomic_load(p, __ATOMIC_RELAXED, __HIP_MEMORY_SCOPE_AGENT); }
; DEV unsigned xb_add(unsigned* p, unsigned v) { return __hip_atomic_fetch_add(p, v, __ATOMIC_RELAXED, __HIP_MEMORY_SCOPE_AGENT); }
; #define XB_SPIN(cond, bar) do { unsigned _sp = 0; while (cond) { __builtin_amdgcn_s_sleep(1); \
;     if ((++_sp & 255u) == 0u) { if (xb_ld(&(bar)[XB_TMO])) break; if (_sp > XB_SPIN_CAP) { atomicAdd(&(bar)[XB_TMO], 1u); break; } } } } while (0)
; DEV void xcd_barrier(const XcdBarrier& b) {
;   asm volatile("s_waitcnt vmcnt(0)" ::: "memory");
;   __syncthreads();
;   if (threadIdx.x == 0) {
;     unsigned* bar = b.bar;
;     __builtin_amdgcn_s_waitcnt(0);
;     unsigned nloc = b.st[0], nx = b.st[1];
;     if (nloc == 0u) { xcd_barrier_complete(bar, b.x, nloc, nx); b.st[0] = nloc; b.st[1] = nx; }
;     const unsigned old = xb_add(&bar[XB_XSUB(b.x)], 1u);
;     const unsigned gen = old / nloc;
;     if (old + 1u == (gen + 1u) * nloc) {
;       __builtin_amdgcn_fence(__ATOMIC_RELEASE, "agent");
;       asm volatile("s_waitcnt vmcnt(0)" ::: "memory");
;       const unsigned og = xb_add(&bar[XB_TOP], 1u);
;       const unsigned tg = og / nx;
;       if (og + 1u == (tg + 1u) * nx) xb_add(&bar[XB_TOPGEN], 1u);
;       else XB_SPIN(xb_ld(&bar[XB_TOPGEN]) == tg, bar);
;       __builtin_amdgcn_fence(__ATOMIC_ACQUIRE, "agent");
;       xb_add(&bar[XB_XGEN(b.x)], 1u);
;       asm volatile("s_waitcnt vmcnt(0)" ::: "memory");
;     } else {
;       XB_SPIN(xb_ld(&bar[XB_XGEN(b.x)]) == gen, bar);
;       __builtin_amdgcn_fence(__ATOMIC_ACQUIRE, "agent");
;       asm volatile("s_waitcnt vmcnt(0)" ::: "memory");
;     }
;   }
;   __syncthreads();
; }
.LBB0_404:
	s_waitcnt vmcnt(0)
	s_waitcnt lgkmcnt(0)
	s_barrier
	s_mov_b64 s[0:1], exec
	v_readlane_b32 s4, v251, 1
	v_readlane_b32 s5, v251, 2
	s_and_b64 s[4:5], s[0:1], s[4:5]
	s_mov_b64 exec, s[4:5]
	s_cbranch_execz .LBB0_452
	s_waitcnt vmcnt(0) expcnt(0) lgkmcnt(0)
	ds_read_b32 v2, v193
	ds_read_b32 v0, v194
	global_atomic_add v3, v[176:177], v195, off sc0
	v_readlane_b32 s14, v251, 3
	v_readlane_b32 s15, v251, 4
	s_waitcnt lgkmcnt(0)
	v_cvt_f32_u32_e32 v1, v2
	v_sub_u32_e32 v4, 0, v2
	v_rcp_iflag_f32_e32 v1, v1
	s_add_u32 s14, s14, 0x3600
	s_addc_u32 s15, s15, 0
	v_mul_f32_e32 v1, 0x4f7ffffe, v1
	v_cvt_u32_f32_e32 v1, v1
	v_mul_lo_u32 v4, v4, v1
	v_mul_hi_u32 v4, v1, v4
	v_add_u32_e32 v1, v1, v4
	s_waitcnt vmcnt(0)
	v_mul_hi_u32 v1, v3, v1
	v_mul_lo_u32 v4, v1, v2
	v_sub_u32_e32 v4, v3, v4
	v_add_u32_e32 v5, 1, v1
	v_cmp_ge_u32_e32 vcc, v4, v2
	v_add_u32_e32 v3, 1, v3
	s_nop 1
	v_cndmask_b32_e32 v1, v1, v5, vcc
	v_sub_u32_e32 v5, v4, v2
	v_cndmask_b32_e32 v4, v4, v5, vcc
	v_add_u32_e32 v5, 1, v1
	v_cmp_ge_u32_e32 vcc, v4, v2
	s_nop 1
	v_cndmask_b32_e32 v1, v1, v5, vcc
	v_mul_lo_u32 v4, v2, v1
	v_add_u32_e32 v2, v4, v2
	v_mul_lo_u32 v5, v1, v0
	v_cmp_eq_u32_e32 vcc, v3, v2
	s_and_saveexec_b64 s[4:5], vcc
	s_cbranch_execz Lxb4_poll
	buffer_wbl2 sc1
	s_waitcnt vmcnt(0)
	global_atomic_add v181, v195, s[14:15]
	global_atomic_add v181, v195, s[14:15] offset:32
	global_atomic_add v181, v195, s[14:15] offset:64
	global_atomic_add v181, v195, s[14:15] offset:96
	global_atomic_add v181, v195, s[14:15] offset:128
	global_atomic_add v181, v195, s[14:15] offset:160
	global_atomic_add v181, v195, s[14:15] offset:192
	global_atomic_add v181, v195, s[14:15] offset:224
	global_atomic_add v181, v195, s[14:15] offset:256
	global_atomic_add v181, v195, s[14:15] offset:288
	global_atomic_add v181, v195, s[14:15] offset:320
	global_atomic_add v181, v195, s[14:15] offset:352
	global_atomic_add v181, v195, s[14:15] offset:384
	global_atomic_add v181, v195, s[14:15] offset:416
	global_atomic_add v181, v195, s[14:15] offset:448
	global_atomic_add v181, v195, s[14:15] offset:480
Lxb4_poll:
	s_or_b64 exec, exec, s[4:5]
	v_subrev_u32_e32 v4, s14, v176
	v_add_u32_e32 v4, 0x2200, v4
	v_lshrrev_b32_e32 v4, 3, v4
	s_mov_b32 s6, 0
Lxb4_spin:
	global_load_dword v0, v4, s[14:15] sc1
	s_waitcnt vmcnt(0)
	v_cmp_ge_u32_e32 vcc, v0, v5
	s_cbranch_vccnz Lxb4_done
	s_sleep 1
	s_add_i32 s6, s6, 1
	s_cmp_lt_u32 s6, 0x400000
	s_cbranch_scc1 Lxb4_spin
Lxb4_done:
	buffer_inv sc1

; DEV unsigned xb_ld(unsigned* p) { return __hip_atomic_load(p, __ATOMIC_RELAXED, __HIP_MEMORY_SCOPE_AGENT); }
; DEV unsigned xb_add(unsigned* p, unsigned v) { return __hip_atomic_fetch_add(p, v, __ATOMIC_RELAXED, __HIP_MEMORY_SCOPE_AGENT); }
; #define XB_SPIN(cond, bar) do { unsigned _sp = 0; while (cond) { __builtin_amdgcn_s_sleep(1); \
;     if ((++_sp & 255u) == 0u) { if (xb_ld(&(bar)[XB_TMO])) break; if (_sp > XB_SPIN_CAP) { atomicAdd(&(bar)[XB_TMO], 1u); break; } } } } while (0)
; DEV void xcd_barrier(const XcdBarrier& b) {
;   asm volatile("s_waitcnt vmcnt(0)" ::: "memory");
;   __syncthreads();
;   if (threadIdx.x == 0) {
;     unsigned* bar = b.bar;
;     __builtin_amdgcn_s_waitcnt(0);
;     unsigned nloc = b.st[0], nx = b.st[1];
;     if (nloc == 0u) { xcd_barrier_complete(bar, b.x, nloc, nx); b.st[0] = nloc; b.st[1] = nx; }
;     const unsigned old = xb_add(&bar[XB_XSUB(b.x)], 1u);
;     const unsigned gen = old / nloc;
;     if (old + 1u == (gen + 1u) * nloc) {
;       __builtin_amdgcn_fence(__ATOMIC_RELEASE, "agent");
;       asm volatile("s_waitcnt vmcnt(0)" ::: "memory");
;       const unsigned og = xb_add(&bar[XB_TOP], 1u);
;       const unsigned tg = og / nx;
;       if (og + 1u == (tg + 1u) * nx) xb_add(&bar[XB_TOPGEN], 1u);
;       else XB_SPIN(xb_ld(&bar[XB_TOPGEN]) == tg, bar);
;       __builtin_amdgcn_fence(__ATOMIC_ACQUIRE, "agent");
;       xb_add(&bar[XB_XGEN(b.x)], 1u);
;       asm volatile("s_waitcnt vmcnt(0)" ::: "memory");
;     } else {
;       XB_SPIN(xb_ld(&bar[XB_XGEN(b.x)]) == gen, bar);
;       __builtin_amdgcn_fence(__ATOMIC_ACQUIRE, "agent");
;       asm volatile("s_waitcnt vmcnt(0)" ::: "memory");
;     }
;   }
;   __syncthreads();
; }
.LBB0_461:
	s_waitcnt vmcnt(0)
	s_waitcnt lgkmcnt(0)
	s_barrier
	s_mov_b64 s[0:1], exec
	v_readlane_b32 s4, v251, 1
	v_readlane_b32 s5, v251, 2
	s_and_b64 s[4:5], s[0:1], s[4:5]
	s_mov_b64 exec, s[4:5]
	s_cbranch_execz .LBB0_509
	s_waitcnt vmcnt(0) expcnt(0) lgkmcnt(0)
	ds_read_b32 v2, v193
	ds_read_b32 v0, v194
	global_atomic_add v3, v[176:177], v195, off sc0
	v_readlane_b32 s14, v251, 3
	v_readlane_b32 s15, v251, 4
	s_waitcnt lgkmcnt(0)
	v_cvt_f32_u32_e32 v1, v2
	v_sub_u32_e32 v4, 0, v2
	v_rcp_iflag_f32_e32 v1, v1
	s_add_u32 s14, s14, 0x3600
	s_addc_u32 s15, s15, 0
	v_mul_f32_e32 v1, 0x4f7ffffe, v1
	v_cvt_u32_f32_e32 v1, v1
	v_mul_lo_u32 v4, v4, v1
	v_mul_hi_u32 v4, v1, v4
	v_add_u32_e32 v1, v1, v4
	s_waitcnt vmcnt(0)
	v_mul_hi_u32 v1, v3, v1
	v_mul_lo_u32 v4, v1, v2
	v_sub_u32_e32 v4, v3, v4
	v_add_u32_e32 v5, 1, v1
	v_cmp_ge_u32_e32 vcc, v4, v2
	v_add_u32_e32 v3, 1, v3
	s_nop 1
	v_cndmask_b32_e32 v1, v1, v5, vcc
	v_sub_u32_e32 v5, v4, v2
	v_cndmask_b32_e32 v4, v4, v5, vcc
	v_add_u32_e32 v5, 1, v1
	v_cmp_ge_u32_e32 vcc, v4, v2
	s_nop 1
	v_cndmask_b32_e32 v1, v1, v5, vcc
	v_mul_lo_u32 v4, v2, v1
	v_add_u32_e32 v2, v4, v2
	v_mul_lo_u32 v5, v1, v0
	v_cmp_eq_u32_e32 vcc, v3, v2
	s_and_saveexec_b64 s[4:5], vcc
	s_cbranch_execz Lxb5_poll
	buffer_wbl2 sc1
	s_waitcnt vmcnt(0)
	global_atomic_add v181, v195, s[14:15]
	global_atomic_add v181, v195, s[14:15] offset:32
	global_atomic_add v181, v195, s[14:15] offset:64
	global_atomic_add v181, v195, s[14:15] offset:96
	global_atomic_add v181, v195, s[14:15] offset:128
	global_atomic_add v181, v195, s[14:15] offset:160
	global_atomic_add v181, v195, s[14:15] offset:192
	global_atomic_add v181, v195, s[14:15] offset:224
	global_atomic_add v181, v195, s[14:15] offset:256
	global_atomic_add v181, v195, s[14:15] offset:288
	global_atomic_add v181, v195, s[14:15] offset:320
	global_atomic_add v181, v195, s[14:15] offset:352
	global_atomic_add v181, v195, s[14:15] offset:384
	global_atomic_add v181, v195, s[14:15] offset:416
	global_atomic_add v181, v195, s[14:15] offset:448
	global_atomic_add v181, v195, s[14:15] offset:480
Lxb5_poll:
	s_or_b64 exec, exec, s[4:5]
	v_subrev_u32_e32 v4, s14, v176
	v_add_u32_e32 v4, 0x2200, v4
	v_lshrrev_b32_e32 v4, 3, v4
	s_mov_b32 s6, 0
Lxb5_spin:
	global_load_dword v0, v4, s[14:15] sc1
	s_waitcnt vmcnt(0)
	v_cmp_ge_u32_e32 vcc, v0, v5
	s_cbranch_vccnz Lxb5_done
	s_sleep 1
	s_add_i32 s6, s6, 1
	s_cmp_lt_u32 s6, 0x400000
	s_cbranch_scc1 Lxb5_spin
Lxb5_done:
	buffer_inv sc1

; DEV unsigned xb_ld(unsigned* p) { return __hip_atomic_load(p, __ATOMIC_RELAXED, __HIP_MEMORY_SCOPE_AGENT); }
; DEV unsigned xb_add(unsigned* p, unsigned v) { return __hip_atomic_fetch_add(p, v, __ATOMIC_RELAXED, __HIP_MEMORY_SCOPE_AGENT); }
; #define XB_SPIN(cond, bar) do { unsigned _sp = 0; while (cond) { __builtin_amdgcn_s_sleep(1); \
;     if ((++_sp & 255u) == 0u) { if (xb_ld(&(bar)[XB_TMO])) break; if (_sp > XB_SPIN_CAP) { atomicAdd(&(bar)[XB_TMO], 1u); break; } } } } while (0)
; DEV void xcd_barrier(const XcdBarrier& b) {
;   asm volatile("s_waitcnt vmcnt(0)" ::: "memory");
;   __syncthreads();
;   if (threadIdx.x == 0) {
;     unsigned* bar = b.bar;
;     __builtin_amdgcn_s_waitcnt(0);
;     unsigned nloc = b.st[0], nx = b.st[1];
;     if (nloc == 0u) { xcd_barrier_complete(bar, b.x, nloc, nx); b.st[0] = nloc; b.st[1] = nx; }
;     const unsigned old = xb_add(&bar[XB_XSUB(b.x)], 1u);
;     const unsigned gen = old / nloc;
;     if (old + 1u == (gen + 1u) * nloc) {
;       __builtin_amdgcn_fence(__ATOMIC_RELEASE, "agent");
;       asm volatile("s_waitcnt vmcnt(0)" ::: "memory");
;       const unsigned og = xb_add(&bar[XB_TOP], 1u);
;       const unsigned tg = og / nx;
;       if (og + 1u == (tg + 1u) * nx) xb_add(&bar[XB_TOPGEN], 1u);
;       else XB_SPIN(xb_ld(&bar[XB_TOPGEN]) == tg, bar);
;       __builtin_amdgcn_fence(__ATOMIC_ACQUIRE, "agent");
;       xb_add(&bar[XB_XGEN(b.x)], 1u);
;       asm volatile("s_waitcnt vmcnt(0)" ::: "memory");
;     } else {
;       XB_SPIN(xb_ld(&bar[XB_XGEN(b.x)]) == gen, bar);
;       __builtin_amdgcn_fence(__ATOMIC_ACQUIRE, "agent");
;       asm volatile("s_waitcnt vmcnt(0)" ::: "memory");
;     }
;   }
;   __syncthreads();
; }
.LBB0_514:
	s_or_b64 exec, exec, s[0:1]
	s_waitcnt vmcnt(0)
	s_waitcnt lgkmcnt(0)
	s_barrier
	s_mov_b64 s[0:1], exec
	v_readlane_b32 s4, v251, 1
	v_readlane_b32 s5, v251, 2
	s_and_b64 s[4:5], s[0:1], s[4:5]
	s_mov_b64 exec, s[4:5]
	s_cbranch_execz .LBB0_562
	s_waitcnt vmcnt(0) expcnt(0) lgkmcnt(0)
	ds_read_b32 v2, v193
	ds_read_b32 v0, v194
	global_atomic_add v3, v[176:177], v195, off sc0
	v_readlane_b32 s14, v251, 3
	v_readlane_b32 s15, v251, 4
	s_waitcnt lgkmcnt(0)
	v_cvt_f32_u32_e32 v1, v2
	v_sub_u32_e32 v4, 0, v2
	v_rcp_iflag_f32_e32 v1, v1
	s_add_u32 s14, s14, 0x3600
	s_addc_u32 s15, s15, 0
	v_mul_f32_e32 v1, 0x4f7ffffe, v1
	v_cvt_u32_f32_e32 v1, v1
	v_mul_lo_u32 v4, v4, v1
	v_mul_hi_u32 v4, v1, v4
	v_add_u32_e32 v1, v1, v4
	s_waitcnt vmcnt(0)
	v_mul_hi_u32 v1, v3, v1
	v_mul_lo_u32 v4, v1, v2
	v_sub_u32_e32 v4, v3, v4
	v_add_u32_e32 v5, 1, v1
	v_cmp_ge_u32_e32 vcc, v4, v2
	v_add_u32_e32 v3, 1, v3
	s_nop 1
	v_cndmask_b32_e32 v1, v1, v5, vcc
	v_sub_u32_e32 v5, v4, v2
	v_cndmask_b32_e32 v4, v4, v5, vcc
	v_add_u32_e32 v5, 1, v1
	v_cmp_ge_u32_e32 vcc, v4, v2
	s_nop 1
	v_cndmask_b32_e32 v1, v1, v5, vcc
	v_mul_lo_u32 v4, v2, v1
	v_add_u32_e32 v2, v4, v2
	v_mul_lo_u32 v5, v1, v0
	v_cmp_eq_u32_e32 vcc, v3, v2
	s_and_saveexec_b64 s[4:5], vcc
	s_cbranch_execz Lxb6_poll
	buffer_wbl2 sc1
	s_waitcnt vmcnt(0)
	global_atomic_add v181, v195, s[14:15]
	global_atomic_add v181, v195, s[14:15] offset:32
	global_atomic_add v181, v195, s[14:15] offset:64
	global_atomic_add v181, v195, s[14:15] offset:96
	global_atomic_add v181, v195, s[14:15] offset:128
	global_atomic_add v181, v195, s[14:15] offset:160
	global_atomic_add v181, v195, s[14:15] offset:192
	global_atomic_add v181, v195, s[14:15] offset:224
	global_atomic_add v181, v195, s[14:15] offset:256
	global_atomic_add v181, v195, s[14:15] offset:288
	global_atomic_add v181, v195, s[14:15] offset:320
	global_atomic_add v181, v195, s[14:15] offset:352
	global_atomic_add v181, v195, s[14:15] offset:384
	global_atomic_add v181, v195, s[14:15] offset:416
	global_atomic_add v181, v195, s[14:15] offset:448
	global_atomic_add v181, v195, s[14:15] offset:480
Lxb6_poll:
	s_or_b64 exec, exec, s[4:5]
	v_subrev_u32_e32 v4, s14, v176
	v_add_u32_e32 v4, 0x2200, v4
	v_lshrrev_b32_e32 v4, 3, v4
	s_mov_b32 s6, 0
Lxb6_spin:
	global_load_dword v0, v4, s[14:15] sc1
	s_waitcnt vmcnt(0)
	v_cmp_ge_u32_e32 vcc, v0, v5
	s_cbranch_vccnz Lxb6_done
	s_sleep 1
	s_add_i32 s6, s6, 1
	s_cmp_lt_u32 s6, 0x400000
	s_cbranch_scc1 Lxb6_spin
Lxb6_done:
	buffer_inv sc1

; DEV unsigned xb_ld(unsigned* p) { return __hip_atomic_load(p, __ATOMIC_RELAXED, __HIP_MEMORY_SCOPE_AGENT); }
; DEV unsigned xb_add(unsigned* p, unsigned v) { return __hip_atomic_fetch_add(p, v, __ATOMIC_RELAXED, __HIP_MEMORY_SCOPE_AGENT); }
; #define XB_SPIN(cond, bar) do { unsigned _sp = 0; while (cond) { __builtin_amdgcn_s_sleep(1); \
;     if ((++_sp & 255u) == 0u) { if (xb_ld(&(bar)[XB_TMO])) break; if (_sp > XB_SPIN_CAP) { atomicAdd(&(bar)[XB_TMO], 1u); break; } } } } while (0)
; DEV void xcd_barrier(const XcdBarrier& b) {
;   asm volatile("s_waitcnt vmcnt(0)" ::: "memory");
;   __syncthreads();
;   if (threadIdx.x == 0) {
;     unsigned* bar = b.bar;
;     __builtin_amdgcn_s_waitcnt(0);
;     unsigned nloc = b.st[0], nx = b.st[1];
;     if (nloc == 0u) { xcd_barrier_complete(bar, b.x, nloc, nx); b.st[0] = nloc; b.st[1] = nx; }
;     const unsigned old = xb_add(&bar[XB_XSUB(b.x)], 1u);
;     const unsigned gen = old / nloc;
;     if (old + 1u == (gen + 1u) * nloc) {
;       __builtin_amdgcn_fence(__ATOMIC_RELEASE, "agent");
;       asm volatile("s_waitcnt vmcnt(0)" ::: "memory");
;       const unsigned og = xb_add(&bar[XB_TOP], 1u);
;       const unsigned tg = og / nx;
;       if (og + 1u == (tg + 1u) * nx) xb_add(&bar[XB_TOPGEN], 1u);
;       else XB_SPIN(xb_ld(&bar[XB_TOPGEN]) == tg, bar);
;       __builtin_amdgcn_fence(__ATOMIC_ACQUIRE, "agent");
;       xb_add(&bar[XB_XGEN(b.x)], 1u);
;       asm volatile("s_waitcnt vmcnt(0)" ::: "memory");
;     } else {
;       XB_SPIN(xb_ld(&bar[XB_XGEN(b.x)]) == gen, bar);
;       __builtin_amdgcn_fence(__ATOMIC_ACQUIRE, "agent");
;       asm volatile("s_waitcnt vmcnt(0)" ::: "memory");
;     }
;   }
;   __syncthreads();
; }
.LBB0_567:
	s_waitcnt vmcnt(0)
	s_waitcnt lgkmcnt(0)
	s_barrier
	s_mov_b64 s[0:1], exec
	v_readlane_b32 s4, v251, 1
	v_readlane_b32 s5, v251, 2
	s_and_b64 s[4:5], s[0:1], s[4:5]
	s_mov_b64 exec, s[4:5]
	s_cbranch_execz .LBB0_615
	s_waitcnt vmcnt(0) expcnt(0) lgkmcnt(0)
	ds_read_b32 v2, v193
	ds_read_b32 v0, v194
	global_atomic_add v3, v[176:177], v195, off sc0
	v_readlane_b32 s14, v251, 3
	v_readlane_b32 s15, v251, 4
	s_waitcnt lgkmcnt(0)
	v_cvt_f32_u32_e32 v1, v2
	v_sub_u32_e32 v4, 0, v2
	v_rcp_iflag_f32_e32 v1, v1
	s_add_u32 s14, s14, 0x3600
	s_addc_u32 s15, s15, 0
	v_mul_f32_e32 v1, 0x4f7ffffe, v1
	v_cvt_u32_f32_e32 v1, v1
	v_mul_lo_u32 v4, v4, v1
	v_mul_hi_u32 v4, v1, v4
	v_add_u32_e32 v1, v1, v4
	s_waitcnt vmcnt(0)
	v_mul_hi_u32 v1, v3, v1
	v_mul_lo_u32 v4, v1, v2
	v_sub_u32_e32 v4, v3, v4
	v_add_u32_e32 v5, 1, v1
	v_cmp_ge_u32_e32 vcc, v4, v2
	v_add_u32_e32 v3, 1, v3
	s_nop 1
	v_cndmask_b32_e32 v1, v1, v5, vcc
	v_sub_u32_e32 v5, v4, v2
	v_cndmask_b32_e32 v4, v4, v5, vcc
	v_add_u32_e32 v5, 1, v1
	v_cmp_ge_u32_e32 vcc, v4, v2
	s_nop 1
	v_cndmask_b32_e32 v1, v1, v5, vcc
	v_mul_lo_u32 v4, v2, v1
	v_add_u32_e32 v2, v4, v2
	v_mul_lo_u32 v5, v1, v0
	v_cmp_eq_u32_e32 vcc, v3, v2
	s_and_saveexec_b64 s[4:5], vcc
	s_cbranch_execz Lxb7_poll
	buffer_wbl2 sc1
	s_waitcnt vmcnt(0)
	global_atomic_add v181, v195, s[14:15]
	global_atomic_add v181, v195, s[14:15] offset:32
	global_atomic_add v181, v195, s[14:15] offset:64
	global_atomic_add v181, v195, s[14:15] offset:96
	global_atomic_add v181, v195, s[14:15] offset:128
	global_atomic_add v181, v195, s[14:15] offset:160
	global_atomic_add v181, v195, s[14:15] offset:192
	global_atomic_add v181, v195, s[14:15] offset:224
	global_atomic_add v181, v195, s[14:15] offset:256
	global_atomic_add v181, v195, s[14:15] offset:288
	global_atomic_add v181, v195, s[14:15] offset:320
	global_atomic_add v181, v195, s[14:15] offset:352
	global_atomic_add v181, v195, s[14:15] offset:384
	global_atomic_add v181, v195, s[14:15] offset:416
	global_atomic_add v181, v195, s[14:15] offset:448
	global_atomic_add v181, v195, s[14:15] offset:480
Lxb7_poll:
	s_or_b64 exec, exec, s[4:5]
	v_subrev_u32_e32 v4, s14, v176
	v_add_u32_e32 v4, 0x2200, v4
	v_lshrrev_b32_e32 v4, 3, v4
	s_mov_b32 s6, 0
Lxb7_spin:
	global_load_dword v0, v4, s[14:15] sc1
	s_waitcnt vmcnt(0)
	v_cmp_ge_u32_e32 vcc, v0, v5
	s_cbranch_vccnz Lxb7_done
	s_sleep 1
	s_add_i32 s6, s6, 1
	s_cmp_lt_u32 s6, 0x400000
	s_cbranch_scc1 Lxb7_spin
Lxb7_done:
	buffer_inv sc1

; DEV unsigned xb_ld(unsigned* p) { return __hip_atomic_load(p, __ATOMIC_RELAXED, __HIP_MEMORY_SCOPE_AGENT); }
; DEV unsigned xb_add(unsigned* p, unsigned v) { return __hip_atomic_fetch_add(p, v, __ATOMIC_RELAXED, __HIP_MEMORY_SCOPE_AGENT); }
; #define XB_SPIN(cond, bar) do { unsigned _sp = 0; while (cond) { __builtin_amdgcn_s_sleep(1); \
;     if ((++_sp & 255u) == 0u) { if (xb_ld(&(bar)[XB_TMO])) break; if (_sp > XB_SPIN_CAP) { atomicAdd(&(bar)[XB_TMO], 1u); break; } } } } while (0)
; DEV void xcd_barrier(const XcdBarrier& b) {
;   asm volatile("s_waitcnt vmcnt(0)" ::: "memory");
;   __syncthreads();
;   if (threadIdx.x == 0) {
;     unsigned* bar = b.bar;
;     __builtin_amdgcn_s_waitcnt(0);
;     unsigned nloc = b.st[0], nx = b.st[1];
;     if (nloc == 0u) { xcd_barrier_complete(bar, b.x, nloc, nx); b.st[0] = nloc; b.st[1] = nx; }
;     const unsigned old = xb_add(&bar[XB_XSUB(b.x)], 1u);
;     const unsigned gen = old / nloc;
;     if (old + 1u == (gen + 1u) * nloc) {
;       __builtin_amdgcn_fence(__ATOMIC_RELEASE, "agent");
;       asm volatile("s_waitcnt vmcnt(0)" ::: "memory");
;       const unsigned og = xb_add(&bar[XB_TOP], 1u);
;       const unsigned tg = og / nx;
;       if (og + 1u == (tg + 1u) * nx) xb_add(&bar[XB_TOPGEN], 1u);
;       else XB_SPIN(xb_ld(&bar[XB_TOPGEN]) == tg, bar);
;       __builtin_amdgcn_fence(__ATOMIC_ACQUIRE, "agent");
;       xb_add(&bar[XB_XGEN(b.x)], 1u);
;       asm volatile("s_waitcnt vmcnt(0)" ::: "memory");
;     } else {
;       XB_SPIN(xb_ld(&bar[XB_XGEN(b.x)]) == gen, bar);
;       __builtin_amdgcn_fence(__ATOMIC_ACQUIRE, "agent");
;       asm volatile("s_waitcnt vmcnt(0)" ::: "memory");
;     }
;   }
;   __syncthreads();
; }
.LBB0_637:
	s_waitcnt vmcnt(0)
	s_waitcnt lgkmcnt(0)
	s_barrier
	s_mov_b64 s[0:1], exec
	v_readlane_b32 s4, v251, 1
	v_readlane_b32 s5, v251, 2
	s_and_b64 s[4:5], s[0:1], s[4:5]
	s_mov_b64 exec, s[4:5]
	s_cbranch_execz .LBB0_685
	s_waitcnt vmcnt(0) expcnt(0) lgkmcnt(0)
	ds_read_b32 v2, v193
	ds_read_b32 v0, v194
	global_atomic_add v3, v[176:177], v195, off sc0
	v_readlane_b32 s14, v251, 3
	v_readlane_b32 s15, v251, 4
	s_waitcnt lgkmcnt(0)
	v_cvt_f32_u32_e32 v1, v2
	v_sub_u32_e32 v4, 0, v2
	v_rcp_iflag_f32_e32 v1, v1
	s_add_u32 s14, s14, 0x3600
	s_addc_u32 s15, s15, 0
	v_mul_f32_e32 v1, 0x4f7ffffe, v1
	v_cvt_u32_f32_e32 v1, v1
	v_mul_lo_u32 v4, v4, v1
	v_mul_hi_u32 v4, v1, v4
	v_add_u32_e32 v1, v1, v4
	s_waitcnt vmcnt(0)
	v_mul_hi_u32 v1, v3, v1
	v_mul_lo_u32 v4, v1, v2
	v_sub_u32_e32 v4, v3, v4
	v_add_u32_e32 v5, 1, v1
	v_cmp_ge_u32_e32 vcc, v4, v2
	v_add_u32_e32 v3, 1, v3
	s_nop 1
	v_cndmask_b32_e32 v1, v1, v5, vcc
	v_sub_u32_e32 v5, v4, v2
	v_cndmask_b32_e32 v4, v4, v5, vcc
	v_add_u32_e32 v5, 1, v1
	v_cmp_ge_u32_e32 vcc, v4, v2
	s_nop 1
	v_cndmask_b32_e32 v1, v1, v5, vcc
	v_mul_lo_u32 v4, v2, v1
	v_add_u32_e32 v2, v4, v2
	v_mul_lo_u32 v5, v1, v0
	v_cmp_eq_u32_e32 vcc, v3, v2
	s_and_saveexec_b64 s[4:5], vcc
	s_cbranch_execz Lxb8_poll
	buffer_wbl2 sc1
	s_waitcnt vmcnt(0)
	global_atomic_add v181, v195, s[14:15]
	global_atomic_add v181, v195, s[14:15] offset:32
	global_atomic_add v181, v195, s[14:15] offset:64
	global_atomic_add v181, v195, s[14:15] offset:96
	global_atomic_add v181, v195, s[14:15] offset:128
	global_atomic_add v181, v195, s[14:15] offset:160
	global_atomic_add v181, v195, s[14:15] offset:192
	global_atomic_add v181, v195, s[14:15] offset:224
	global_atomic_add v181, v195, s[14:15] offset:256
	global_atomic_add v181, v195, s[14:15] offset:288
	global_atomic_add v181, v195, s[14:15] offset:320
	global_atomic_add v181, v195, s[14:15] offset:352
	global_atomic_add v181, v195, s[14:15] offset:384
	global_atomic_add v181, v195, s[14:15] offset:416
	global_atomic_add v181, v195, s[14:15] offset:448
	global_atomic_add v181, v195, s[14:15] offset:480
Lxb8_poll:
	s_or_b64 exec, exec, s[4:5]
	v_subrev_u32_e32 v4, s14, v176
	v_add_u32_e32 v4, 0x2200, v4
	v_lshrrev_b32_e32 v4, 3, v4
	s_mov_b32 s6, 0
Lxb8_spin:
	global_load_dword v0, v4, s[14:15] sc1
	s_waitcnt vmcnt(0)
	v_cmp_ge_u32_e32 vcc, v0, v5
	s_cbranch_vccnz Lxb8_done
	s_sleep 1
	s_add_i32 s6, s6, 1
	s_cmp_lt_u32 s6, 0x400000
	s_cbranch_scc1 Lxb8_spin
Lxb8_done:
	buffer_inv sc1

; DEV unsigned xb_ld(unsigned* p) { return __hip_atomic_load(p, __ATOMIC_RELAXED, __HIP_MEMORY_SCOPE_AGENT); }
; DEV unsigned xb_add(unsigned* p, unsigned v) { return __hip_atomic_fetch_add(p, v, __ATOMIC_RELAXED, __HIP_MEMORY_SCOPE_AGENT); }
; #define XB_SPIN(cond, bar) do { unsigned _sp = 0; while (cond) { __builtin_amdgcn_s_sleep(1); \
;     if ((++_sp & 255u) == 0u) { if (xb_ld(&(bar)[XB_TMO])) break; if (_sp > XB_SPIN_CAP) { atomicAdd(&(bar)[XB_TMO], 1u); break; } } } } while (0)
; DEV void xcd_barrier(const XcdBarrier& b) {
;   asm volatile("s_waitcnt vmcnt(0)" ::: "memory");
;   __syncthreads();
;   if (threadIdx.x == 0) {
;     unsigned* bar = b.bar;
;     __builtin_amdgcn_s_waitcnt(0);
;     unsigned nloc = b.st[0], nx = b.st[1];
;     if (nloc == 0u) { xcd_barrier_complete(bar, b.x, nloc, nx); b.st[0] = nloc; b.st[1] = nx; }
;     const unsigned old = xb_add(&bar[XB_XSUB(b.x)], 1u);
;     const unsigned gen = old / nloc;
;     if (old + 1u == (gen + 1u) * nloc) {
;       __builtin_amdgcn_fence(__ATOMIC_RELEASE, "agent");
;       asm volatile("s_waitcnt vmcnt(0)" ::: "memory");
;       const unsigned og = xb_add(&bar[XB_TOP], 1u);
;       const unsigned tg = og / nx;
;       if (og + 1u == (tg + 1u) * nx) xb_add(&bar[XB_TOPGEN], 1u);
;       else XB_SPIN(xb_ld(&bar[XB_TOPGEN]) == tg, bar);
;       __builtin_amdgcn_fence(__ATOMIC_ACQUIRE, "agent");
;       xb_add(&bar[XB_XGEN(b.x)], 1u);
;       asm volatile("s_waitcnt vmcnt(0)" ::: "memory");
;     } else {
;       XB_SPIN(xb_ld(&bar[XB_XGEN(b.x)]) == gen, bar);
;       __builtin_amdgcn_fence(__ATOMIC_ACQUIRE, "agent");
;       asm volatile("s_waitcnt vmcnt(0)" ::: "memory");
;     }
;   }
;   __syncthreads();
; }
.LBB0_778:
	s_waitcnt vmcnt(0) expcnt(0) lgkmcnt(0)
	ds_read_b32 v2, v193
	ds_read_b32 v0, v194
	global_atomic_add v3, v[176:177], v195, off sc0
	v_readlane_b32 s16, v251, 3
	v_readlane_b32 s17, v251, 4
	s_waitcnt lgkmcnt(0)
	v_cvt_f32_u32_e32 v1, v2
	v_sub_u32_e32 v4, 0, v2
	v_rcp_iflag_f32_e32 v1, v1
	s_add_u32 s16, s16, 0x3600
	s_addc_u32 s17, s17, 0
	v_mul_f32_e32 v1, 0x4f7ffffe, v1
	v_cvt_u32_f32_e32 v1, v1
	v_mul_lo_u32 v4, v4, v1
	v_mul_hi_u32 v4, v1, v4
	v_add_u32_e32 v1, v1, v4
	s_waitcnt vmcnt(0)
	v_mul_hi_u32 v1, v3, v1
	v_mul_lo_u32 v4, v1, v2
	v_sub_u32_e32 v4, v3, v4
	v_add_u32_e32 v5, 1, v1
	v_cmp_ge_u32_e32 vcc, v4, v2
	v_add_u32_e32 v3, 1, v3
	s_nop 1
	v_cndmask_b32_e32 v1, v1, v5, vcc
	v_sub_u32_e32 v5, v4, v2
	v_cndmask_b32_e32 v4, v4, v5, vcc
	v_add_u32_e32 v5, 1, v1
	v_cmp_ge_u32_e32 vcc, v4, v2
	s_nop 1
	v_cndmask_b32_e32 v1, v1, v5, vcc
	v_mul_lo_u32 v4, v2, v1
	v_add_u32_e32 v2, v4, v2
	v_mul_lo_u32 v5, v1, v0
	v_cmp_eq_u32_e32 vcc, v3, v2
	s_and_saveexec_b64 s[14:15], vcc
	s_cbranch_execz Lxb9_poll
	buffer_wbl2 sc1
	s_waitcnt vmcnt(0)
	global_atomic_add v181, v195, s[16:17]
	global_atomic_add v181, v195, s[16:17] offset:32
	global_atomic_add v181, v195, s[16:17] offset:64
	global_atomic_add v181, v195, s[16:17] offset:96
	global_atomic_add v181, v195, s[16:17] offset:128
	global_atomic_add v181, v195, s[16:17] offset:160
	global_atomic_add v181, v195, s[16:17] offset:192
	global_atomic_add v181, v195, s[16:17] offset:224
	global_atomic_add v181, v195, s[16:17] offset:256
	global_atomic_add v181, v195, s[16:17] offset:288
	global_atomic_add v181, v195, s[16:17] offset:320
	global_atomic_add v181, v195, s[16:17] offset:352
	global_atomic_add v181, v195, s[16:17] offset:384
	global_atomic_add v181, v195, s[16:17] offset:416
	global_atomic_add v181, v195, s[16:17] offset:448
	global_atomic_add v181, v195, s[16:17] offset:480
Lxb9_poll:
	s_or_b64 exec, exec, s[14:15]
	v_subrev_u32_e32 v4, s16, v176
	v_add_u32_e32 v4, 0x2200, v4
	v_lshrrev_b32_e32 v4, 3, v4
	s_mov_b32 s6, 0
Lxb9_spin:
	global_load_dword v0, v4, s[16:17] sc1
	s_waitcnt vmcnt(0)
	v_cmp_ge_u32_e32 vcc, v0, v5
	s_cbranch_vccnz Lxb9_done
	s_sleep 1
	s_add_i32 s6, s6, 1
	s_cmp_lt_u32 s6, 0x400000
	s_cbranch_scc1 Lxb9_spin
Lxb9_done:
	s_mov_b64 s[4:5], 0
	s_getpc_b64 s[98:99]
